# baseline (speedup 1.0000x reference)
; #define LAS __attribute__((address_space(3)))
; #define SREP(bit) for (int rep_ = 0; rep_ < (((SUBDUP >> (bit)) & 1) ? 2 : 1); ++rep_)
; __device__ __forceinline__ void rw_scan4(const int tid, LAS float* lds, const float* RW, int task, int ntasks, int mode, const float* SIN, float* PQ, float* Y) {
;     const int slot = tid >> 7, sl = tid & 127, kp = sl & 7, rg = sl >> 3;
;     const bool active = task < ntasks;
;     int head = 0, c = 0, kind = 2;
;     if (active) { if (mode == 0) { kind = task & 1; head = (task >> 1) & 7; c = task >> 4; } else { head = task & 7; c = task >> 3; } }
;     const int t0 = c * CHL;
;     f32x2 s[4][4];
;     if (kind == 2 && active) {
;         const float* ip = SIN + (size_t)(head * NCH + c) * 4096 + (rg * 4) * 64 + kp * 8;
; #pragma unroll
;         for (int j = 0; j < 4; ++j) { const f32x4 i0 = *(const f32x4*)(ip + j * 64), i1 = *(const f32x4*)(ip + j * 64 + 4);
;             s[j][0] = (f32x2){i0.x, i0.y}; s[j][1] = (f32x2){i0.z, i0.w}; s[j][2] = (f32x2){i1.x, i1.y}; s[j][3] = (f32x2){i1.z, i1.w}; }
;     } else {
; #pragma unroll
;         for (int j = 0; j < 4; ++j)
; #pragma unroll
;             for (int i = 0; i < 4; ++i) { const int kk = kp * 8 + 2 * i, rr = rg * 4 + j; s[j][i] = (f32x2){(kind == 1 && kk == rr) ? 1.f : 0.f, (kind == 1 && kk + 1 == rr) ? 1.f : 0.f}; }
;     }
;     LAS float* sb = lds + slot * (2 * 6 * TB * 64);
;     const int srow = sl >> 4, sc4 = sl & 15;
;     const float* gsrc = RW + (size_t)(t0 + srow) * GW + head * 64 + sc4 * 4;
;     f32x4 st[6];
; __global__ void __launch_bounds__(NTHR, 2) hymba_fwd(Args args) {
;     ...
;             SREP(4) for (int tb = 0; tb < NCH * 8 * 2; tb += 4 * G) rw_scan4(tid, ldsf, WSP(float, WS_RW), tb + bid * 4 + (tid >> 7), NCH * 8 * 2, 0, nullptr, WSP(float, WS_PQ), nullptr);
.LBB0_210:
	v_readlane_b32 s0, v254, 29
	s_cmp_gt_i32 s0, 4
	s_mov_b64 s[0:1], -1
	s_cbranch_scc0 .LBB0_347
	v_readlane_b32 s0, v254, 29
	s_cmp_gt_i32 s0, 5
	s_mov_b64 s[0:1], -1
	s_cbranch_scc0 .LBB0_314
	v_readlane_b32 s0, v254, 44
	s_cmp_ge_u32 s0, 4
	s_cbranch_scc0 .Lp6_prio_done
	s_setprio 1
.Lp6_prio_done:
	s_waitcnt vmcnt(5)
	v_and_b32_e32 v1, 7, v148
	s_waitcnt vmcnt(4)
	v_bfe_u32 v6, v148, 3, 4
	v_ashrrev_i32_e32 v0, 7, v148
	v_lshlrev_b32_e32 v2, 3, v1
	v_lshlrev_b32_e32 v3, 2, v6
	s_movk_i32 s4, 0x6000
	v_lshlrev_b32_e32 v130, 2, v148
	v_lshl_add_u32 v131, s44, 2, v0
	v_and_b32_e32 v132, 1, v0
	v_cmp_eq_u32_e64 s[38:39], v2, v3
	v_or_b32_e32 v2, 4, v2
	v_mul_lo_u32 v7, v0, s4
	v_bfe_u32 v133, v148, 4, 3
	v_and_b32_e32 v0, 60, v130
	v_readlane_b32 s0, v254, 32
	v_cmp_eq_u32_e64 s[40:41], v2, v3
	v_add_u32_e32 v3, 0, v7
	v_lshlrev_b32_e32 v4, 2, v0
	v_lshlrev_b32_e32 v2, 5, v1
	v_lshlrev_b32_e32 v1, 8, v133
	v_readlane_b32 s1, v254, 33
	v_add3_u32 v134, v3, v4, v1
	v_lshlrev_b32_e32 v4, 10, v6
	v_mov_b32_e32 v5, v144
	s_load_dwordx16 s[48:63], s[0:1], 0x38
	s_waitcnt lgkmcnt(0)
	v_lshl_add_u64 v[4:5], s[18:19], 0, v[4:5]
	v_mov_b32_e32 v3, v144
	v_lshl_add_u64 v[4:5], v[4:5], 0, v[2:3]
	s_mov_b64 s[4:5], 0x28300000
	s_add_u32 s0, s18, 0x16200000
	v_lshl_add_u64 v[92:93], v[4:5], 0, s[4:5]
	v_lshl_or_b32 v1, v6, 4, v7
	v_readlane_b32 s4, v254, 15
	s_addc_u32 s1, s19, 0
	s_lshl_b32 s14, s45, 2
	v_add_u32_e32 v135, s4, v1
	v_or_b32_e32 v1, v7, v2
	s_add_i32 s4, 0, 0x800
	v_cmp_eq_u32_e64 s[42:43], 1, v132
	v_add_u32_e32 v136, s4, v1
	s_mov_b32 s15, 0
	v_lshlrev_b32_e32 v94, 2, v0
	s_branch .LBB0_214

; #define SREP(bit) for (int rep_ = 0; rep_ < (((SUBDUP >> (bit)) & 1) ? 2 : 1); ++rep_)
; __device__ __forceinline__ void rg_scan_seg(const int tid, const float* RGA, const float* RGB, float* RGC, float* RGH, float* SEG, int seg) {
;     const int c = tid;
;     float h = 0.f, A = 1.f;
;     for (int t = seg * RGSEGL; t < (seg + 1) * RGSEGL; t += 8) {
;         float a[8], b[8];
; #pragma unroll
;         for (int i = 0; i < 8; ++i) { a[i] = RGA[(size_t)(t + i) * GW + c]; b[i] = RGB[(size_t)(t + i) * GW + c]; }
; #pragma unroll
;         for (int i = 0; i < 8; ++i) { h = a[i] * h + b[i]; A *= a[i]; RGH[(size_t)(t + i) * GW + c] = h; RGC[(size_t)(t + i) * GW + c] = A; }
;     }
;     SEG[seg * GW + c] = A; SEG[(RGSEG + seg) * GW + c] = h;
; }
; __global__ void __launch_bounds__(NTHR, 2) hymba_fwd(Args args) {
;     ...
;             SREP(6) for (int sgi = bid; sgi < RGSEG; sgi += G) rg_scan_seg(tid, WSP(float, WS_RGA), WSP(float, WS_RGB), WSP(float, WS_RGC), WSP(float, WS_RGH), WSP(float, WS_SEG), sgi);
.LBB0_306:
	s_setprio 0
	v_readlane_b32 s0, v254, 39
	s_cmpk_gt_i32 s0, 0x7f
	v_readlane_b32 s45, v254, 38
	s_waitcnt lgkmcnt(0)
	s_barrier
	s_cbranch_scc1 .LBB0_313
	v_readlane_b32 s44, v254, 39
	s_waitcnt vmcnt(0)
	v_cmp_gt_u32_e32 vcc, 0x80, v148
	s_and_saveexec_b64 s[4:5], vcc
	s_cbranch_execz .Lrgs_done
	v_lshlrev_b32_e32 v0, 4, v148

; __global__ void __launch_bounds__(NTHR, 2) hymba_fwd(Args args) {
;     ...
;         } else if (k == 5) {
;             FILL_L();
;             const float* P = WSP(float, WS_UP);
;             if (l + 1 < NL) for (int i = bid * NTHR + tid; i < T; i += G * NTHR) WSP(float, WS_SS)[i] = 0.f;
.LBB0_314:
	s_and_b64 vcc, exec, s[0:1]
	s_cbranch_vccz .LBB0_346
	v_readlane_b32 s0, v254, 44
	s_cmp_ge_u32 s0, 4
	s_cbranch_scc0 .Lp5_prio_done
	s_setprio 1
.Lp5_prio_done:
	v_readlane_b32 s0, v254, 32
	v_readlane_b32 s1, v254, 33
	s_load_dwordx8 s[4:11], s[0:1], 0x38
	s_waitcnt lgkmcnt(0)
	v_writelane_b32 v254, s4, 47
	s_nop 1
	v_writelane_b32 v254, s5, 48
	v_writelane_b32 v254, s6, 49
	v_writelane_b32 v254, s7, 50
	v_writelane_b32 v254, s8, 51
	v_writelane_b32 v254, s9, 52
	v_writelane_b32 v254, s10, 53
	v_writelane_b32 v254, s11, 54
	s_load_dwordx2 s[4:5], s[0:1], 0x58
	s_waitcnt lgkmcnt(0)
	v_writelane_b32 v254, s4, 55
	s_nop 1
	v_writelane_b32 v254, s5, 56
	s_load_dwordx8 s[4:11], s[0:1], 0x88
	s_load_dwordx2 s[34:35], s[0:1], 0xf0
	s_load_dwordx2 s[22:23], s[0:1], 0xb8
	s_load_dwordx4 s[80:83], s[0:1], 0xe0
	s_load_dwordx2 s[14:15], s[0:1], 0x138
	s_load_dwordx4 s[24:27], s[0:1], 0x128
	s_waitcnt lgkmcnt(0)
	v_writelane_b32 v254, s14, 57
	s_nop 1
	v_writelane_b32 v254, s15, 58
	v_writelane_b32 v254, s24, 59
	s_nop 1
	v_writelane_b32 v254, s25, 60
	v_writelane_b32 v254, s26, 61
	v_writelane_b32 v254, s27, 62
	s_load_dwordx8 s[24:31], s[0:1], 0x108
	s_waitcnt lgkmcnt(0)
	v_writelane_b32 v254, s24, 63
	s_nop 1
	v_writelane_b32 v255, s25, 0
	v_writelane_b32 v255, s26, 1
	v_writelane_b32 v255, s27, 2
	v_writelane_b32 v255, s28, 3
	v_writelane_b32 v255, s29, 4
	v_writelane_b32 v255, s30, 5
	v_readlane_b32 s0, v254, 30
	v_writelane_b32 v255, s31, 6
	s_cmp_gt_i32 s0, 0
	v_readlane_b32 s1, v254, 31
	s_cbranch_scc1 .LBB0_325
	s_waitcnt vmcnt(5)
	v_lshl_add_u32 v0, s44, 9, v148
	s_movk_i32 s0, 0x2000
	v_cmp_gt_i32_e32 vcc, s0, v0
	s_and_saveexec_b64 s[0:1], vcc
	s_cbranch_execz .LBB0_324
	s_add_u32 s20, s18, 0x29b00000
	s_addc_u32 s21, s19, 0
	s_lshl_b32 s14, s45, 9
	s_waitcnt vmcnt(4)
	v_cvt_f32_u32_e32 v4, s14
	v_add_u32_e32 v1, s14, v0
	s_movk_i32 s12, 0x2000
	v_cmp_gt_i32_e32 vcc, s12, v1
	v_rcp_iflag_f32_e32 v4, v4
	s_sub_i32 s12, 0, s14
	v_max_i32_e32 v2, 0x2000, v1
	v_cndmask_b32_e64 v3, 1, 2, vcc
	v_mul_f32_e32 v4, 0x4f7ffffe, v4
	v_cvt_u32_f32_e32 v4, v4
	v_subb_co_u32_e32 v2, vcc, v2, v1, vcc
	s_mov_b64 s[26:27], -1
	v_mul_lo_u32 v5, s12, v4
	v_mul_hi_u32 v5, v4, v5
	v_add_u32_e32 v4, v4, v5
	v_mul_hi_u32 v4, v2, v4
	v_mul_lo_u32 v5, v4, s14
	v_sub_u32_e32 v2, v2, v5
	v_cmp_le_u32_e32 vcc, s14, v2
	v_add_u32_e32 v5, 1, v4
	s_nop 0
	v_cndmask_b32_e32 v4, v4, v5, vcc
	v_subrev_u32_e32 v5, s14, v2
	v_cndmask_b32_e32 v2, v2, v5, vcc
	v_cmp_le_u32_e32 vcc, s14, v2
	v_add_u32_e32 v2, 1, v4
	s_nop 0
	v_cndmask_b32_e32 v2, v4, v2, vcc
	v_add_u32_e32 v4, v3, v2
	v_cmp_lt_u32_e32 vcc, 1, v4
	s_and_saveexec_b64 s[24:25], vcc
	s_cbranch_execz .LBB0_321
	v_and_b32_e32 v5, -2, v4
	s_lshl_b32 s12, s45, 10
	s_mov_b32 s15, s12
	s_mov_b64 s[26:27], 0
	v_mov_b32_e32 v6, v5
	v_mov_b64_e32 v[2:3], v[0:1]
	s_waitcnt vmcnt(0)

; #define SREP(bit) for (int rep_ = 0; rep_ < (((SUBDUP >> (bit)) & 1) ? 2 : 1); ++rep_)
; __global__ void __launch_bounds__(NTHR, 2) hymba_fwd(Args args) {
;     ...
;             __syncthreads();
;     ...
;             SREP(3) for (int u = bid; u < 32 * 16; u += G) s5_unit<false>(tid, ldsf, P, L, WSP(f32x2, WS_E), WSP(float, WS_VF), WSP(bf16, WS_VB), u);
;     ...
;             __syncthreads();
.LBB0_452:
	s_setprio 0
	s_barrier
	s_cbranch_execz .LBB0_348
	s_branch .LBB0_457
